# P10 EpiFinal: 7 of the second-half residual loads hoisted next to the first-half loads (copied into place later)
# speedup vs baseline: 1.0157x; 1.0157x over previous
.LBB0_958:
	s_lshl_b32 s52, s57, 8
	v_add_u32_e32 v168, s52, v179
	v_lshl_or_b32 v170, s12, 8, v181
	v_ashrrev_i32_e32 v171, 31, v170
	v_ashrrev_i32_e32 v169, 31, v168
	v_lshl_add_u64 v[128:129], v[170:171], 1, s[96:97]
	v_lshlrev_b64 v[130:131], 11, v[168:169]
	v_lshl_add_u64 v[172:173], v[128:129], 0, v[130:131]
	v_or_b32_e32 v130, 16, v168
	v_ashrrev_i32_e32 v131, 31, v130
	v_lshlrev_b64 v[130:131], 11, v[130:131]
	v_mov_b32_e32 v174, v214
	v_lshl_add_u64 v[130:131], v[128:129], 0, v[130:131]
	global_load_dwordx4 v[202:205], v[172:173], off
	global_load_dwordx4 v[206:209], v[172:173], off offset:256
	global_load_dwordx4 v[148:151], v[130:131], off
	global_load_dwordx4 v[144:147], v[130:131], off offset:256
	v_or_b32_e32 v130, 32, v168
	v_ashrrev_i32_e32 v131, 31, v130
	v_lshlrev_b64 v[130:131], 11, v[130:131]
	v_lshl_add_u64 v[130:131], v[128:129], 0, v[130:131]
	global_load_dwordx4 v[140:143], v[130:131], off
	global_load_dwordx4 v[136:139], v[130:131], off offset:256
	v_or_b32_e32 v130, 48, v168
	v_ashrrev_i32_e32 v131, 31, v130
	v_lshlrev_b64 v[130:131], 11, v[130:131]
	v_lshl_add_u64 v[128:129], v[128:129], 0, v[130:131]
	global_load_dwordx4 v[132:135], v[128:129], off
	s_nop 0
	global_load_dwordx4 v[128:131], v[128:129], off offset:256
	s_mov_b64 s[98:99], 0x40000
	v_lshl_add_u64 v[252:253], v[172:173], 0, s[98:99]
	global_load_dwordx4 v[216:219], v[252:253], off
	global_load_dwordx4 v[220:223], v[252:253], off offset:256
	s_mov_b64 s[98:99], 0x8000
	v_lshl_add_u64 v[252:253], v[252:253], 0, s[98:99]
	global_load_dwordx4 v[224:227], v[252:253], off
	global_load_dwordx4 v[228:231], v[252:253], off offset:256
	v_lshl_add_u64 v[252:253], v[252:253], 0, s[98:99]
	global_load_dwordx4 v[232:235], v[252:253], off
	global_load_dwordx4 v[244:247], v[252:253], off offset:256
	v_lshl_add_u64 v[252:253], v[252:253], 0, s[98:99]
	global_load_dwordx4 v[248:251], v[252:253], off
	v_and_b32_e32 v176, 64, v215
	v_xor_b32_e32 v175, 16, v215
	v_add_u32_e32 v176, 64, v176
	v_cmp_lt_i32_e32 vcc, v175, v176
	v_xor_b32_e32 v177, 32, v215
	s_nop 0
	v_cndmask_b32_e32 v175, v215, v175, vcc
	v_cmp_lt_i32_e32 vcc, v177, v176
	v_lshlrev_b32_e32 v175, 2, v175
	s_nop 0
	v_cndmask_b32_e32 v176, v215, v177, vcc
	v_lshlrev_b32_e32 v176, 2, v176
	s_waitcnt vmcnt(7)
	v_lshlrev_b32_e32 v210, 16, v202
	v_and_b32_e32 v211, 0xffff0000, v202
	v_lshlrev_b32_e32 v202, 16, v203
	v_and_b32_e32 v203, 0xffff0000, v203
	v_pk_add_f32 v[126:127], v[126:127], v[202:203]
	v_pk_add_f32 v[124:125], v[124:125], v[210:211]
	v_lshlrev_b32_e32 v212, 16, v204
	v_and_b32_e32 v213, 0xffff0000, v204
	v_mul_f32_e32 v177, v125, v125
	v_mul_f32_e32 v202, v127, v127
	v_pk_add_f32 v[120:121], v[120:121], v[212:213]
	v_fmac_f32_e32 v177, v124, v124
	v_fmac_f32_e32 v202, v126, v126
	v_lshlrev_b32_e32 v204, 16, v205
	v_and_b32_e32 v205, 0xffff0000, v205
	v_add_f32_e32 v177, v177, v202
	v_mul_f32_e32 v202, v121, v121
	v_pk_add_f32 v[122:123], v[122:123], v[204:205]
	v_fmac_f32_e32 v202, v120, v120
	v_add_f32_e32 v177, v202, v177
	v_mul_f32_e32 v202, v123, v123
	v_fmac_f32_e32 v202, v122, v122
	v_add_f32_e32 v177, v202, v177
	v_lshlrev_b32_e32 v202, 16, v206
	v_and_b32_e32 v203, 0xffff0000, v206
	v_lshlrev_b32_e32 v204, 16, v207
	v_and_b32_e32 v205, 0xffff0000, v207
	v_pk_add_f32 v[118:119], v[118:119], v[204:205]
	v_pk_add_f32 v[116:117], v[116:117], v[202:203]
	v_lshlrev_b32_e32 v206, 16, v208
	v_and_b32_e32 v207, 0xffff0000, v208
	v_mul_f32_e32 v202, v117, v117
	v_mul_f32_e32 v203, v119, v119
	v_pk_add_f32 v[112:113], v[112:113], v[206:207]
	v_fmac_f32_e32 v202, v116, v116
	v_fmac_f32_e32 v203, v118, v118
	v_lshlrev_b32_e32 v208, 16, v209
	v_and_b32_e32 v209, 0xffff0000, v209
	v_add_f32_e32 v202, v202, v203
	v_mul_f32_e32 v203, v113, v113
	v_pk_add_f32 v[114:115], v[114:115], v[208:209]
	v_fmac_f32_e32 v203, v112, v112
	v_add_f32_e32 v202, v203, v202
	v_mul_f32_e32 v203, v115, v115
	v_fmac_f32_e32 v203, v114, v114
	v_add_f32_e32 v202, v203, v202
	v_add_f32_e32 v177, v177, v202
	ds_bpermute_b32 v202, v175, v177
	s_waitcnt lgkmcnt(0)
	v_add_f32_e32 v177, v177, v202
	ds_bpermute_b32 v202, v176, v177
	s_and_saveexec_b64 s[14:15], s[0:1]
	s_cbranch_execz .LBB0_960
	s_waitcnt lgkmcnt(0)
	v_add_f32_e32 v177, v177, v202
	ds_write_b32 v201, v177

.LBB0_966:
	s_or_b64 exec, exec, s[14:15]
	v_add_co_u32_e32 v66, vcc, 0x40000, v172
	s_mov_b64 s[14:15], 0x40000
	s_nop 0
	v_addc_co_u32_e32 v67, vcc, 0, v173, vcc
	s_waitcnt lgkmcnt(0)
	v_lshl_add_u64 v[64:65], v[172:173], 0, s[14:15]
	s_waitcnt vmcnt(0)
	v_mov_b64_e32 v[202:203], v[216:217]
	v_mov_b64_e32 v[204:205], v[218:219]
	v_mov_b64_e32 v[206:207], v[220:221]
	v_mov_b64_e32 v[208:209], v[222:223]
	v_add_co_u32_e32 v66, vcc, 0x48000, v172
	s_mov_b64 s[14:15], 0x48000
	s_nop 0
	v_addc_co_u32_e32 v67, vcc, 0, v173, vcc
	v_lshl_add_u64 v[64:65], v[172:173], 0, s[14:15]
	v_mov_b64_e32 v[84:85], v[224:225]
	v_mov_b64_e32 v[86:87], v[226:227]
	v_mov_b64_e32 v[80:81], v[228:229]
	v_mov_b64_e32 v[82:83], v[230:231]
	v_add_co_u32_e32 v66, vcc, 0x50000, v172
	s_mov_b64 s[14:15], 0x50000
	s_nop 0
	v_addc_co_u32_e32 v67, vcc, 0, v173, vcc
	v_lshl_add_u64 v[64:65], v[172:173], 0, s[14:15]
	v_mov_b64_e32 v[76:77], v[232:233]
	v_mov_b64_e32 v[78:79], v[234:235]
	v_mov_b64_e32 v[72:73], v[244:245]
	v_mov_b64_e32 v[74:75], v[246:247]
	s_mov_b64 s[14:15], 0x58000
	v_add_co_u32_e32 v66, vcc, 0x58000, v172
	v_lshl_add_u64 v[64:65], v[172:173], 0, s[14:15]
	s_nop 0
	v_addc_co_u32_e32 v67, vcc, 0, v173, vcc
	v_mov_b64_e32 v[68:69], v[248:249]
	v_mov_b64_e32 v[70:71], v[250:251]
	s_nop 0
	global_load_dwordx4 v[64:67], v[64:65], off offset:256
	s_waitcnt vmcnt(7)
	v_lshlrev_b32_e32 v172, 16, v202
	v_and_b32_e32 v173, 0xffff0000, v202
	v_lshlrev_b32_e32 v202, 16, v203
	v_and_b32_e32 v203, 0xffff0000, v203
	v_pk_add_f32 v[62:63], v[62:63], v[202:203]
	v_pk_add_f32 v[60:61], v[60:61], v[172:173]
	v_lshlrev_b32_e32 v210, 16, v204
	v_and_b32_e32 v211, 0xffff0000, v204
	v_mul_f32_e32 v172, v61, v61
	v_mul_f32_e32 v173, v63, v63
	v_pk_add_f32 v[56:57], v[56:57], v[210:211]
	v_fmac_f32_e32 v172, v60, v60
	v_fmac_f32_e32 v173, v62, v62
	v_lshlrev_b32_e32 v204, 16, v205
	v_and_b32_e32 v205, 0xffff0000, v205
	v_add_f32_e32 v172, v172, v173
	v_mul_f32_e32 v173, v57, v57
	v_pk_add_f32 v[58:59], v[58:59], v[204:205]
	v_fmac_f32_e32 v173, v56, v56
	v_add_f32_e32 v172, v173, v172
	v_mul_f32_e32 v173, v59, v59
	v_fmac_f32_e32 v173, v58, v58
	v_add_f32_e32 v177, v173, v172
	s_waitcnt vmcnt(6)
	v_lshlrev_b32_e32 v172, 16, v206
	v_and_b32_e32 v173, 0xffff0000, v206
	v_lshlrev_b32_e32 v202, 16, v207
	v_and_b32_e32 v203, 0xffff0000, v207
	v_pk_add_f32 v[54:55], v[54:55], v[202:203]
	v_pk_add_f32 v[52:53], v[52:53], v[172:173]
	v_lshlrev_b32_e32 v204, 16, v208
	v_and_b32_e32 v205, 0xffff0000, v208
	v_mul_f32_e32 v172, v53, v53
	v_mul_f32_e32 v173, v55, v55
	v_pk_add_f32 v[48:49], v[48:49], v[204:205]
	v_fmac_f32_e32 v172, v52, v52
	v_fmac_f32_e32 v173, v54, v54
	v_lshlrev_b32_e32 v206, 16, v209
	v_and_b32_e32 v207, 0xffff0000, v209
	v_add_f32_e32 v172, v172, v173
	v_mul_f32_e32 v173, v49, v49
	v_pk_add_f32 v[50:51], v[50:51], v[206:207]
	v_fmac_f32_e32 v173, v48, v48
	v_add_f32_e32 v172, v173, v172
	v_mul_f32_e32 v173, v51, v51
	v_fmac_f32_e32 v173, v50, v50
	v_add_f32_e32 v172, v173, v172
	v_add_f32_e32 v172, v177, v172
	ds_bpermute_b32 v173, v175, v172
	s_waitcnt lgkmcnt(0)
	v_add_f32_e32 v172, v172, v173
	ds_bpermute_b32 v173, v176, v172
	s_and_saveexec_b64 s[14:15], s[0:1]
	s_cbranch_execz .LBB0_968
	s_waitcnt lgkmcnt(0)
	v_add_f32_e32 v172, v172, v173
	ds_write_b32 v201, v172 offset:2048
